# SSM pass-1 step loop rewritten by hand (in-place packed scan, two u fragments in flight)
# speedup vs baseline: 1.0275x; 1.0071x over previous
; __device__ __forceinline__ f32x2 pk_fma(f32x2 a, f32x2 b, f32x2 c) { return __builtin_elementwise_fma(a, b, c); }
; template <bool FINAL>
; __device__ __forceinline__ void ssm_item(const Args& a, LAS unsigned char* lds, int item, int wave, int lane) {
;     ...
;     bf16x8 uf = *(const bf16x8*)up;
;     u32x2 uu0 = (u32x2){0u, 0u}, uu1 = (u32x2){0u, 0u};
;     if (FINAL) { uu0 = *(const u32x2*)ue; uu1 = *(const u32x2*)(ue + (size_t)SEQ * DM); }
;     for (int st = 0; st < nsteps; ++st) {
;         bf16x8 ufn = uf; u32x2 un0 = uu0, un1 = uu1;
;         if (st + 1 < nsteps) { ufn = *(const bf16x8*)(up + (size_t)(st + 1) * 8 * DM);
;             if (FINAL) { un0 = *(const u32x2*)(ue + (size_t)(st + 1) * 8 * DM); un1 = *(const u32x2*)(ue + (size_t)(st + 1) * 8 * DM + (size_t)SEQ * DM); } }
;         f32x16 X[4];
; #pragma unroll
;         for (int k = 0; k < 4; ++k) { f32x16 z;
; #pragma unroll
;             for (int e = 0; e < 16; ++e) z[e] = 0.f;
;             X[k] = __builtin_amdgcn_mfma_f32_32x32x16_bf16(uf, bbf[k], z, 0, 0, 0); }
; #pragma unroll
;         for (int t = 0; t < 8; ++t) {
;             const f32x2 x0r = (f32x2){X[0][2 * t], X[0][2 * t + 1]}, x0i = (f32x2){X[1][2 * t], X[1][2 * t + 1]}, x1r = (f32x2){X[2][2 * t], X[2][2 * t + 1]}, x1i = (f32x2){X[3][2 * t], X[3][2 * t + 1]};
;             const f32x2 n0r = pk_fma(a0x, s0r, pk_fma(na0y, s0i, x0r)), n0i = pk_fma(a0x, s0i, pk_fma(a0y, s0r, x0i));
;             const f32x2 n1r = pk_fma(a1x, s1r, pk_fma(na1y, s1i, x1r)), n1i = pk_fma(a1x, s1i, pk_fma(a1y, s1r, x1i));
;             s0r = n0r; s0i = n0i; s1r = n1r; s1i = n1i;
.LBB0_267:
	v_lshlrev_b32_e32 v0, 11, v0
	v_mov_b32_e32 v1, v85
	v_lshl_add_u64 v[2:3], s[52:53], 0, v[0:1]
	s_lshl_b32 s24, s10, 5
	s_mov_b32 s25, s11
	v_lshl_add_u64 v[2:3], v[2:3], 0, s[24:25]
	v_lshl_add_u64 v[2:3], v[2:3], 0, v[90:91]
	global_load_dwordx4 v[80:83], v[2:3], off
	s_lshl_b32 s17, s19, 4
	s_and_b32 s17, s17, 0x380
	s_add_i32 s17, s18, s17
	s_lshl_b32 s24, s17, 1
	s_waitcnt vmcnt(2)
	v_xor_b32_e32 v106, 0x80000000, v99
	s_waitcnt vmcnt(1)
	v_xor_b32_e32 v108, 0x80000000, v97
	v_lshl_add_u64 v[0:1], v[0:1], 0, s[24:25]
	v_mov_b32_e32 v48, 0
	v_mov_b32_e32 v100, v98
	v_mov_b32_e32 v101, v98
	v_mov_b32_e32 v98, v99
	v_mov_b32_e32 v107, v106
	v_mov_b32_e32 v102, v96
	v_mov_b32_e32 v103, v96
	v_mov_b32_e32 v96, v97
	v_mov_b32_e32 v109, v108
	s_add_i32 s16, s16, 1
	v_lshl_add_u64 v[110:111], v[88:89], 0, v[0:1]
	v_mov_b32_e32 v49, v48
	v_mov_b32_e32 v50, v48
	v_mov_b32_e32 v51, v48
	v_mov_b32_e32 v112, v48
	v_mov_b32_e32 v113, v48
	v_mov_b32_e32 v114, v48
	v_mov_b32_e32 v115, v48
	global_load_dwordx4 v[132:135], v[110:111], off
	v_lshl_add_u64 v[110:111], v[110:111], 0, s[12:13]
	s_add_i32 s29, s16, 1
	s_lshr_b32 s29, s29, 1
	v_mov_b32_e32 v120, 0
	v_mov_b32_e32 v121, 0
	v_mov_b32_e32 v122, 0
	v_mov_b32_e32 v123, 0
	v_mov_b32_e32 v124, 0
	v_mov_b32_e32 v125, 0
	v_mov_b32_e32 v126, 0
	v_mov_b32_e32 v127, 0
.Lssm1_step:
	s_waitcnt vmcnt(1)
	v_mfma_f32_32x32x16_bf16 v[0:15], v[80:83], v[68:71], 0
	v_mfma_f32_32x32x16_bf16 v[16:31], v[80:83], v[72:75], 0
	v_mfma_f32_32x32x16_bf16 v[32:47], v[80:83], v[76:79], 0
	v_mfma_f32_32x32x16_bf16 v[48:63], v[80:83], v[64:67], 0
	s_nop 15
	global_load_dwordx4 v[80:83], v[110:111], off
	v_lshl_add_u64 v[110:111], v[110:111], 0, s[12:13]
	v_pk_fma_f32 v[0:1], v[106:107], v[122:123], v[0:1]
	v_pk_fma_f32 v[16:17], v[98:99], v[120:121], v[16:17]
	v_pk_fma_f32 v[32:33], v[108:109], v[126:127], v[32:33]
	v_pk_fma_f32 v[48:49], v[96:97], v[124:125], v[48:49]
	v_pk_fma_f32 v[0:1], v[100:101], v[120:121], v[0:1]
	v_pk_fma_f32 v[16:17], v[100:101], v[122:123], v[16:17]
	v_pk_fma_f32 v[32:33], v[102:103], v[124:125], v[32:33]
	v_pk_fma_f32 v[48:49], v[102:103], v[126:127], v[48:49]
	v_pk_fma_f32 v[2:3], v[106:107], v[16:17], v[2:3]
	v_pk_fma_f32 v[18:19], v[98:99], v[0:1], v[18:19]
	v_pk_fma_f32 v[34:35], v[108:109], v[48:49], v[34:35]
	v_pk_fma_f32 v[50:51], v[96:97], v[32:33], v[50:51]
	v_pk_fma_f32 v[2:3], v[100:101], v[0:1], v[2:3]
	v_pk_fma_f32 v[18:19], v[100:101], v[16:17], v[18:19]
	v_pk_fma_f32 v[34:35], v[102:103], v[32:33], v[34:35]
	v_pk_fma_f32 v[50:51], v[102:103], v[48:49], v[50:51]
	v_pk_fma_f32 v[4:5], v[106:107], v[18:19], v[4:5]
	v_pk_fma_f32 v[20:21], v[98:99], v[2:3], v[20:21]
	v_pk_fma_f32 v[36:37], v[108:109], v[50:51], v[36:37]
	v_pk_fma_f32 v[52:53], v[96:97], v[34:35], v[52:53]
	v_pk_fma_f32 v[4:5], v[100:101], v[2:3], v[4:5]
	v_pk_fma_f32 v[20:21], v[100:101], v[18:19], v[20:21]
	v_pk_fma_f32 v[36:37], v[102:103], v[34:35], v[36:37]
	v_pk_fma_f32 v[52:53], v[102:103], v[50:51], v[52:53]
	v_pk_fma_f32 v[6:7], v[106:107], v[20:21], v[6:7]
	v_pk_fma_f32 v[22:23], v[98:99], v[4:5], v[22:23]
	v_pk_fma_f32 v[38:39], v[108:109], v[52:53], v[38:39]
	v_pk_fma_f32 v[54:55], v[96:97], v[36:37], v[54:55]
	v_pk_fma_f32 v[6:7], v[100:101], v[4:5], v[6:7]
	v_pk_fma_f32 v[22:23], v[100:101], v[20:21], v[22:23]
	v_pk_fma_f32 v[38:39], v[102:103], v[36:37], v[38:39]
	v_pk_fma_f32 v[54:55], v[102:103], v[52:53], v[54:55]
	v_pk_fma_f32 v[8:9], v[106:107], v[22:23], v[8:9]
	v_pk_fma_f32 v[24:25], v[98:99], v[6:7], v[24:25]
	v_pk_fma_f32 v[40:41], v[108:109], v[54:55], v[40:41]
	v_pk_fma_f32 v[56:57], v[96:97], v[38:39], v[56:57]
	v_pk_fma_f32 v[8:9], v[100:101], v[6:7], v[8:9]
	v_pk_fma_f32 v[24:25], v[100:101], v[22:23], v[24:25]
	v_pk_fma_f32 v[40:41], v[102:103], v[38:39], v[40:41]
	v_pk_fma_f32 v[56:57], v[102:103], v[54:55], v[56:57]
	v_pk_fma_f32 v[10:11], v[106:107], v[24:25], v[10:11]
	v_pk_fma_f32 v[26:27], v[98:99], v[8:9], v[26:27]
	v_pk_fma_f32 v[42:43], v[108:109], v[56:57], v[42:43]
	v_pk_fma_f32 v[58:59], v[96:97], v[40:41], v[58:59]
	v_pk_fma_f32 v[10:11], v[100:101], v[8:9], v[10:11]
	v_pk_fma_f32 v[26:27], v[100:101], v[24:25], v[26:27]
	v_pk_fma_f32 v[42:43], v[102:103], v[40:41], v[42:43]
	v_pk_fma_f32 v[58:59], v[102:103], v[56:57], v[58:59]
	v_pk_fma_f32 v[12:13], v[106:107], v[26:27], v[12:13]
	v_pk_fma_f32 v[28:29], v[98:99], v[10:11], v[28:29]
	v_pk_fma_f32 v[44:45], v[108:109], v[58:59], v[44:45]
	v_pk_fma_f32 v[60:61], v[96:97], v[42:43], v[60:61]
	v_pk_fma_f32 v[12:13], v[100:101], v[10:11], v[12:13]
	v_pk_fma_f32 v[28:29], v[100:101], v[26:27], v[28:29]
	v_pk_fma_f32 v[44:45], v[102:103], v[42:43], v[44:45]
	v_pk_fma_f32 v[60:61], v[102:103], v[58:59], v[60:61]
	v_pk_fma_f32 v[14:15], v[106:107], v[28:29], v[14:15]
	v_pk_fma_f32 v[30:31], v[98:99], v[12:13], v[30:31]
	v_pk_fma_f32 v[46:47], v[108:109], v[60:61], v[46:47]
	v_pk_fma_f32 v[62:63], v[96:97], v[44:45], v[62:63]
	v_pk_fma_f32 v[120:121], v[100:101], v[12:13], v[14:15]
	v_pk_fma_f32 v[122:123], v[100:101], v[28:29], v[30:31]
	v_pk_fma_f32 v[124:125], v[102:103], v[44:45], v[46:47]
	v_pk_fma_f32 v[126:127], v[102:103], v[60:61], v[62:63]
	s_waitcnt vmcnt(1)
; #define LAS __attribute__((address_space(3)))
; __device__ __forceinline__ unsigned cvt_pk(float lo, float hi) { unsigned r; asm volatile("v_cvt_pk_bf16_f32 %0, %1, %2" : "=v"(r) : "v"(lo), "v"(hi)); return r; }
; __device__ __forceinline__ f32x2 pk_fma(f32x2 a, f32x2 b, f32x2 c) { return __builtin_elementwise_fma(a, b, c); }
; template <bool FINAL>
; __device__ __forceinline__ void ssm_item(const Args& a, LAS unsigned char* lds, int item, int wave, int lane) {
;     ...
;     for (int st = 0; st < nsteps; ++st) {
;         bf16x8 ufn = uf; u32x2 un0 = uu0, un1 = uu1;
;         if (st + 1 < nsteps) { ufn = *(const bf16x8*)(up + (size_t)(st + 1) * 8 * DM);
;             if (FINAL) { un0 = *(const u32x2*)(ue + (size_t)(st + 1) * 8 * DM); un1 = *(const u32x2*)(ue + (size_t)(st + 1) * 8 * DM + (size_t)SEQ * DM); } }
;         f32x16 X[4];
; #pragma unroll
;         for (int k = 0; k < 4; ++k) { f32x16 z;
; #pragma unroll
;             for (int e = 0; e < 16; ++e) z[e] = 0.f;
;             X[k] = __builtin_amdgcn_mfma_f32_32x32x16_bf16(uf, bbf[k], z, 0, 0, 0); }
; #pragma unroll
;         for (int t = 0; t < 8; ++t) {
;             const f32x2 x0r = (f32x2){X[0][2 * t], X[0][2 * t + 1]}, x0i = (f32x2){X[1][2 * t], X[1][2 * t + 1]}, x1r = (f32x2){X[2][2 * t], X[2][2 * t + 1]}, x1i = (f32x2){X[3][2 * t], X[3][2 * t + 1]};
;             const f32x2 n0r = pk_fma(a0x, s0r, pk_fma(na0y, s0i, x0r)), n0i = pk_fma(a0x, s0i, pk_fma(a0y, s0r, x0i));
;             const f32x2 n1r = pk_fma(a1x, s1r, pk_fma(na1y, s1i, x1r)), n1i = pk_fma(a1x, s1i, pk_fma(a1y, s1r, x1i));
;             s0r = n0r; s0i = n0i; s1r = n1r; s1i = n1i;
;             if (FINAL) {
;                 LAS unsigned char* r0 = sl + ((hi * 2 + 0) * 8 + t) * SP; LAS unsigned char* r1 = sl + ((hi * 2 + 1) * 8 + t) * SP;
;                 *(LAS unsigned*)(r0 + j * 4) = cvt_pk(n0r.x, n0i.x); *(LAS unsigned*)(r0 + (32 + j) * 4) = cvt_pk(n1r.x, n1i.x);
;                 *(LAS unsigned*)(r1 + j * 4) = cvt_pk(n0r.y, n0i.y); *(LAS unsigned*)(r1 + (32 + j) * 4) = cvt_pk(n1r.y, n1i.y); }
;         }
	v_mfma_f32_32x32x16_bf16 v[0:15], v[132:135], v[68:71], 0
	v_mfma_f32_32x32x16_bf16 v[16:31], v[132:135], v[72:75], 0
	v_mfma_f32_32x32x16_bf16 v[32:47], v[132:135], v[76:79], 0
	v_mfma_f32_32x32x16_bf16 v[48:63], v[132:135], v[64:67], 0
	s_add_i32 s29, s29, -1
	s_nop 15
	global_load_dwordx4 v[132:135], v[110:111], off
	v_lshl_add_u64 v[110:111], v[110:111], 0, s[12:13]
	v_pk_fma_f32 v[0:1], v[106:107], v[122:123], v[0:1]
	v_pk_fma_f32 v[16:17], v[98:99], v[120:121], v[16:17]
	v_pk_fma_f32 v[32:33], v[108:109], v[126:127], v[32:33]
	v_pk_fma_f32 v[48:49], v[96:97], v[124:125], v[48:49]
	v_pk_fma_f32 v[0:1], v[100:101], v[120:121], v[0:1]
	v_pk_fma_f32 v[16:17], v[100:101], v[122:123], v[16:17]
	v_pk_fma_f32 v[32:33], v[102:103], v[124:125], v[32:33]
	v_pk_fma_f32 v[48:49], v[102:103], v[126:127], v[48:49]
	v_pk_fma_f32 v[2:3], v[106:107], v[16:17], v[2:3]
	v_pk_fma_f32 v[18:19], v[98:99], v[0:1], v[18:19]
	v_pk_fma_f32 v[34:35], v[108:109], v[48:49], v[34:35]
	v_pk_fma_f32 v[50:51], v[96:97], v[32:33], v[50:51]
	v_pk_fma_f32 v[2:3], v[100:101], v[0:1], v[2:3]
	v_pk_fma_f32 v[18:19], v[100:101], v[16:17], v[18:19]
	v_pk_fma_f32 v[34:35], v[102:103], v[32:33], v[34:35]
	v_pk_fma_f32 v[50:51], v[102:103], v[48:49], v[50:51]
	v_pk_fma_f32 v[4:5], v[106:107], v[18:19], v[4:5]
	v_pk_fma_f32 v[20:21], v[98:99], v[2:3], v[20:21]
	v_pk_fma_f32 v[36:37], v[108:109], v[50:51], v[36:37]
	v_pk_fma_f32 v[52:53], v[96:97], v[34:35], v[52:53]
	v_pk_fma_f32 v[4:5], v[100:101], v[2:3], v[4:5]
	v_pk_fma_f32 v[20:21], v[100:101], v[18:19], v[20:21]
	v_pk_fma_f32 v[36:37], v[102:103], v[34:35], v[36:37]
	v_pk_fma_f32 v[52:53], v[102:103], v[50:51], v[52:53]
	v_pk_fma_f32 v[6:7], v[106:107], v[20:21], v[6:7]
	v_pk_fma_f32 v[22:23], v[98:99], v[4:5], v[22:23]
	v_pk_fma_f32 v[38:39], v[108:109], v[52:53], v[38:39]
	v_pk_fma_f32 v[54:55], v[96:97], v[36:37], v[54:55]
	v_pk_fma_f32 v[6:7], v[100:101], v[4:5], v[6:7]
	v_pk_fma_f32 v[22:23], v[100:101], v[20:21], v[22:23]
	v_pk_fma_f32 v[38:39], v[102:103], v[36:37], v[38:39]
	v_pk_fma_f32 v[54:55], v[102:103], v[52:53], v[54:55]
	v_pk_fma_f32 v[8:9], v[106:107], v[22:23], v[8:9]
	v_pk_fma_f32 v[24:25], v[98:99], v[6:7], v[24:25]
	v_pk_fma_f32 v[40:41], v[108:109], v[54:55], v[40:41]
	v_pk_fma_f32 v[56:57], v[96:97], v[38:39], v[56:57]
	v_pk_fma_f32 v[8:9], v[100:101], v[6:7], v[8:9]
	v_pk_fma_f32 v[24:25], v[100:101], v[22:23], v[24:25]
	v_pk_fma_f32 v[40:41], v[102:103], v[38:39], v[40:41]
	v_pk_fma_f32 v[56:57], v[102:103], v[54:55], v[56:57]
	v_pk_fma_f32 v[10:11], v[106:107], v[24:25], v[10:11]
	v_pk_fma_f32 v[26:27], v[98:99], v[8:9], v[26:27]
	v_pk_fma_f32 v[42:43], v[108:109], v[56:57], v[42:43]
	v_pk_fma_f32 v[58:59], v[96:97], v[40:41], v[58:59]
	v_pk_fma_f32 v[10:11], v[100:101], v[8:9], v[10:11]
	v_pk_fma_f32 v[26:27], v[100:101], v[24:25], v[26:27]
	v_pk_fma_f32 v[42:43], v[102:103], v[40:41], v[42:43]
	v_pk_fma_f32 v[58:59], v[102:103], v[56:57], v[58:59]
	v_pk_fma_f32 v[12:13], v[106:107], v[26:27], v[12:13]
	v_pk_fma_f32 v[28:29], v[98:99], v[10:11], v[28:29]
	v_pk_fma_f32 v[44:45], v[108:109], v[58:59], v[44:45]
	v_pk_fma_f32 v[60:61], v[96:97], v[42:43], v[60:61]
	v_pk_fma_f32 v[12:13], v[100:101], v[10:11], v[12:13]
	v_pk_fma_f32 v[28:29], v[100:101], v[26:27], v[28:29]
	v_pk_fma_f32 v[44:45], v[102:103], v[42:43], v[44:45]
	v_pk_fma_f32 v[60:61], v[102:103], v[58:59], v[60:61]
	v_pk_fma_f32 v[14:15], v[106:107], v[28:29], v[14:15]
	v_pk_fma_f32 v[30:31], v[98:99], v[12:13], v[30:31]
	v_pk_fma_f32 v[46:47], v[108:109], v[60:61], v[46:47]
	v_pk_fma_f32 v[62:63], v[96:97], v[44:45], v[62:63]
	v_pk_fma_f32 v[120:121], v[100:101], v[12:13], v[14:15]
	v_pk_fma_f32 v[122:123], v[100:101], v[28:29], v[30:31]
	v_pk_fma_f32 v[124:125], v[102:103], v[44:45], v[46:47]
	v_pk_fma_f32 v[126:127], v[102:103], v[60:61], v[62:63]
	s_cmp_lg_u32 s29, 0
	s_cbranch_scc1 .Lssm1_step
	v_mov_b64_e32 v[0:1], v[120:121]
	v_mov_b64_e32 v[4:5], v[122:123]
	v_mov_b64_e32 v[2:3], v[124:125]
	v_mov_b64_e32 v[6:7], v[126:127]
	s_mov_b64 s[16:17], -1
	s_and_b64 vcc, exec, s[14:15]
	s_cbranch_vccnz .LBB0_271
	s_andn2_b64 vcc, exec, s[16:17]
	s_cbranch_vccnz .LBB0_264
	s_branch .LBB0_272
